# phase 2 pooling: window prefix rows loaded as one exec-masked batch instead of a dependent load per iteration
# baseline (speedup 1.0000x reference)
.LBB0_265:
	s_andn2_saveexec_b64 s[0:1], s[0:1]
	s_cbranch_execz .LBB0_271
	s_waitcnt vmcnt(0)
	v_mov_b32_e32 v15, 0
	v_cmp_ne_u32_e32 vcc, 0, v27
	v_mov_b32_e32 v14, v15
	v_mov_b32_e32 v17, v15
	v_mov_b32_e32 v16, v15
	v_mov_b32_e32 v125, v15
	v_mov_b32_e32 v124, v15
	v_mov_b32_e32 v13, v15
	v_mov_b32_e32 v12, v15
	s_and_saveexec_b64 s[26:27], vcc
	s_cbranch_execz .LBB0_270
	v_lshlrev_b64 v[2:3], 1, v[132:133]
	s_movk_i32 s28, 0x1400
	v_mad_i64_i32 v[2:3], s[28:29], v178, s28, v[2:3]
	v_mov_b32_e32 v14, 0
	v_lshl_add_u64 v[2:3], s[22:23], 0, v[2:3]
	v_mov_b32_e32 v15, v14
	v_mov_b32_e32 v12, v14
	v_mov_b32_e32 v13, v14
	v_mov_b32_e32 v124, v14
	v_mov_b32_e32 v125, v14
	v_mov_b32_e32 v16, v14
	v_mov_b32_e32 v17, v14
	s_movk_i32 s30, 0xec00
	s_mov_b32 s31, -1
	s_mov_b64 vcc, exec
	global_load_dwordx4 v[6:9], v[2:3], off
	v_cmp_le_u32_e64 s[28:29], 4, v150
	v_lshl_add_u64 v[10:11], v[2:3], 0, s[30:31]
	s_and_b64 exec, exec, s[28:29]
	global_load_dwordx4 v[68:71], v[10:11], off
	v_lshl_add_u64 v[10:11], v[10:11], 0, s[30:31]
	global_load_dwordx4 v[72:75], v[10:11], off
	v_cmp_le_u32_e64 s[28:29], 8, v150
	v_lshl_add_u64 v[10:11], v[10:11], 0, s[30:31]
	s_and_b64 exec, exec, s[28:29]
	global_load_dwordx4 v[76:79], v[10:11], off
	v_lshl_add_u64 v[10:11], v[10:11], 0, s[30:31]
	global_load_dwordx4 v[80:83], v[10:11], off
	v_lshl_add_u64 v[10:11], v[10:11], 0, s[30:31]
	global_load_dwordx4 v[84:87], v[10:11], off
	v_lshl_add_u64 v[10:11], v[10:11], 0, s[30:31]
	global_load_dwordx4 v[88:91], v[10:11], off
	v_cmp_le_u32_e64 s[28:29], 16, v150
	v_lshl_add_u64 v[10:11], v[10:11], 0, s[30:31]
	s_and_b64 exec, exec, s[28:29]
	global_load_dwordx4 v[92:95], v[10:11], off
	v_lshl_add_u64 v[10:11], v[10:11], 0, s[30:31]
	global_load_dwordx4 v[96:99], v[10:11], off
	v_lshl_add_u64 v[10:11], v[10:11], 0, s[30:31]
	global_load_dwordx4 v[100:103], v[10:11], off
	v_lshl_add_u64 v[10:11], v[10:11], 0, s[30:31]
	global_load_dwordx4 v[104:107], v[10:11], off
	v_lshl_add_u64 v[10:11], v[10:11], 0, s[30:31]
	global_load_dwordx4 v[108:111], v[10:11], off
	v_lshl_add_u64 v[10:11], v[10:11], 0, s[30:31]
	global_load_dwordx4 v[112:115], v[10:11], off
	v_lshl_add_u64 v[10:11], v[10:11], 0, s[30:31]
	global_load_dwordx4 v[116:119], v[10:11], off
	v_lshl_add_u64 v[10:11], v[10:11], 0, s[30:31]
	global_load_dwordx4 v[120:123], v[10:11], off
	s_mov_b64 exec, vcc
	s_waitcnt vmcnt(0)
	v_lshlrev_b32_e32 v10, 16, v6
	v_and_b32_e32 v11, 0xffff0000, v6
	v_pk_add_f32 v[12:13], v[12:13], v[10:11]
	v_lshlrev_b32_e32 v4, 16, v7
	v_and_b32_e32 v5, 0xffff0000, v7
	v_pk_add_f32 v[124:125], v[124:125], v[4:5]
	v_lshlrev_b32_e32 v10, 16, v8
	v_and_b32_e32 v11, 0xffff0000, v8
	v_pk_add_f32 v[16:17], v[16:17], v[10:11]
	v_lshlrev_b32_e32 v4, 16, v9
	v_and_b32_e32 v5, 0xffff0000, v9
	v_pk_add_f32 v[14:15], v[14:15], v[4:5]
	v_cmp_le_u32_e64 s[28:29], 4, v150
	s_nop 0
	s_and_b64 exec, exec, s[28:29]
	v_lshlrev_b32_e32 v10, 16, v68
	v_and_b32_e32 v11, 0xffff0000, v68
	v_pk_add_f32 v[12:13], v[12:13], v[10:11]
	v_lshlrev_b32_e32 v4, 16, v69
	v_and_b32_e32 v5, 0xffff0000, v69
	v_pk_add_f32 v[124:125], v[124:125], v[4:5]
	v_lshlrev_b32_e32 v10, 16, v70
	v_and_b32_e32 v11, 0xffff0000, v70
	v_pk_add_f32 v[16:17], v[16:17], v[10:11]
	v_lshlrev_b32_e32 v4, 16, v71
	v_and_b32_e32 v5, 0xffff0000, v71
	v_pk_add_f32 v[14:15], v[14:15], v[4:5]
	v_lshlrev_b32_e32 v10, 16, v72
	v_and_b32_e32 v11, 0xffff0000, v72
	v_pk_add_f32 v[12:13], v[12:13], v[10:11]
	v_lshlrev_b32_e32 v4, 16, v73
	v_and_b32_e32 v5, 0xffff0000, v73
	v_pk_add_f32 v[124:125], v[124:125], v[4:5]
	v_lshlrev_b32_e32 v10, 16, v74
	v_and_b32_e32 v11, 0xffff0000, v74
	v_pk_add_f32 v[16:17], v[16:17], v[10:11]
	v_lshlrev_b32_e32 v4, 16, v75
	v_and_b32_e32 v5, 0xffff0000, v75
	v_pk_add_f32 v[14:15], v[14:15], v[4:5]
	v_cmp_le_u32_e64 s[28:29], 8, v150
	s_nop 0
	s_and_b64 exec, exec, s[28:29]
	v_lshlrev_b32_e32 v10, 16, v76
	v_and_b32_e32 v11, 0xffff0000, v76
	v_pk_add_f32 v[12:13], v[12:13], v[10:11]
	v_lshlrev_b32_e32 v4, 16, v77
	v_and_b32_e32 v5, 0xffff0000, v77
	v_pk_add_f32 v[124:125], v[124:125], v[4:5]
	v_lshlrev_b32_e32 v10, 16, v78
	v_and_b32_e32 v11, 0xffff0000, v78
	v_pk_add_f32 v[16:17], v[16:17], v[10:11]
	v_lshlrev_b32_e32 v4, 16, v79
	v_and_b32_e32 v5, 0xffff0000, v79
	v_pk_add_f32 v[14:15], v[14:15], v[4:5]
	v_lshlrev_b32_e32 v10, 16, v80
	v_and_b32_e32 v11, 0xffff0000, v80
	v_pk_add_f32 v[12:13], v[12:13], v[10:11]
	v_lshlrev_b32_e32 v4, 16, v81
	v_and_b32_e32 v5, 0xffff0000, v81
	v_pk_add_f32 v[124:125], v[124:125], v[4:5]
	v_lshlrev_b32_e32 v10, 16, v82
	v_and_b32_e32 v11, 0xffff0000, v82
	v_pk_add_f32 v[16:17], v[16:17], v[10:11]
	v_lshlrev_b32_e32 v4, 16, v83
	v_and_b32_e32 v5, 0xffff0000, v83
	v_pk_add_f32 v[14:15], v[14:15], v[4:5]
	v_lshlrev_b32_e32 v10, 16, v84
	v_and_b32_e32 v11, 0xffff0000, v84
	v_pk_add_f32 v[12:13], v[12:13], v[10:11]
	v_lshlrev_b32_e32 v4, 16, v85
	v_and_b32_e32 v5, 0xffff0000, v85
	v_pk_add_f32 v[124:125], v[124:125], v[4:5]
	v_lshlrev_b32_e32 v10, 16, v86
	v_and_b32_e32 v11, 0xffff0000, v86
	v_pk_add_f32 v[16:17], v[16:17], v[10:11]
	v_lshlrev_b32_e32 v4, 16, v87
	v_and_b32_e32 v5, 0xffff0000, v87
	v_pk_add_f32 v[14:15], v[14:15], v[4:5]
	v_lshlrev_b32_e32 v10, 16, v88
	v_and_b32_e32 v11, 0xffff0000, v88
	v_pk_add_f32 v[12:13], v[12:13], v[10:11]
	v_lshlrev_b32_e32 v4, 16, v89
	v_and_b32_e32 v5, 0xffff0000, v89
	v_pk_add_f32 v[124:125], v[124:125], v[4:5]
	v_lshlrev_b32_e32 v10, 16, v90
	v_and_b32_e32 v11, 0xffff0000, v90
	v_pk_add_f32 v[16:17], v[16:17], v[10:11]
	v_lshlrev_b32_e32 v4, 16, v91
	v_and_b32_e32 v5, 0xffff0000, v91
	v_pk_add_f32 v[14:15], v[14:15], v[4:5]
	v_cmp_le_u32_e64 s[28:29], 16, v150
	s_nop 0
	s_and_b64 exec, exec, s[28:29]
	v_lshlrev_b32_e32 v10, 16, v92
	v_and_b32_e32 v11, 0xffff0000, v92
	v_pk_add_f32 v[12:13], v[12:13], v[10:11]
	v_lshlrev_b32_e32 v4, 16, v93
	v_and_b32_e32 v5, 0xffff0000, v93
	v_pk_add_f32 v[124:125], v[124:125], v[4:5]
	v_lshlrev_b32_e32 v10, 16, v94
	v_and_b32_e32 v11, 0xffff0000, v94
	v_pk_add_f32 v[16:17], v[16:17], v[10:11]
	v_lshlrev_b32_e32 v4, 16, v95
	v_and_b32_e32 v5, 0xffff0000, v95
	v_pk_add_f32 v[14:15], v[14:15], v[4:5]
	v_lshlrev_b32_e32 v10, 16, v96
	v_and_b32_e32 v11, 0xffff0000, v96
	v_pk_add_f32 v[12:13], v[12:13], v[10:11]
	v_lshlrev_b32_e32 v4, 16, v97
	v_and_b32_e32 v5, 0xffff0000, v97
	v_pk_add_f32 v[124:125], v[124:125], v[4:5]
	v_lshlrev_b32_e32 v10, 16, v98
	v_and_b32_e32 v11, 0xffff0000, v98
	v_pk_add_f32 v[16:17], v[16:17], v[10:11]
	v_lshlrev_b32_e32 v4, 16, v99
	v_and_b32_e32 v5, 0xffff0000, v99
	v_pk_add_f32 v[14:15], v[14:15], v[4:5]
	v_lshlrev_b32_e32 v10, 16, v100
	v_and_b32_e32 v11, 0xffff0000, v100
	v_pk_add_f32 v[12:13], v[12:13], v[10:11]
	v_lshlrev_b32_e32 v4, 16, v101
	v_and_b32_e32 v5, 0xffff0000, v101
	v_pk_add_f32 v[124:125], v[124:125], v[4:5]
	v_lshlrev_b32_e32 v10, 16, v102
	v_and_b32_e32 v11, 0xffff0000, v102
	v_pk_add_f32 v[16:17], v[16:17], v[10:11]
	v_lshlrev_b32_e32 v4, 16, v103
	v_and_b32_e32 v5, 0xffff0000, v103
	v_pk_add_f32 v[14:15], v[14:15], v[4:5]
	v_lshlrev_b32_e32 v10, 16, v104
	v_and_b32_e32 v11, 0xffff0000, v104
	v_pk_add_f32 v[12:13], v[12:13], v[10:11]
	v_lshlrev_b32_e32 v4, 16, v105
	v_and_b32_e32 v5, 0xffff0000, v105
	v_pk_add_f32 v[124:125], v[124:125], v[4:5]
	v_lshlrev_b32_e32 v10, 16, v106
	v_and_b32_e32 v11, 0xffff0000, v106
	v_pk_add_f32 v[16:17], v[16:17], v[10:11]
	v_lshlrev_b32_e32 v4, 16, v107
	v_and_b32_e32 v5, 0xffff0000, v107
	v_pk_add_f32 v[14:15], v[14:15], v[4:5]
	v_lshlrev_b32_e32 v10, 16, v108
	v_and_b32_e32 v11, 0xffff0000, v108
	v_pk_add_f32 v[12:13], v[12:13], v[10:11]
	v_lshlrev_b32_e32 v4, 16, v109
	v_and_b32_e32 v5, 0xffff0000, v109
	v_pk_add_f32 v[124:125], v[124:125], v[4:5]
	v_lshlrev_b32_e32 v10, 16, v110
	v_and_b32_e32 v11, 0xffff0000, v110
	v_pk_add_f32 v[16:17], v[16:17], v[10:11]
	v_lshlrev_b32_e32 v4, 16, v111
	v_and_b32_e32 v5, 0xffff0000, v111
	v_pk_add_f32 v[14:15], v[14:15], v[4:5]
	v_lshlrev_b32_e32 v10, 16, v112
	v_and_b32_e32 v11, 0xffff0000, v112
	v_pk_add_f32 v[12:13], v[12:13], v[10:11]
	v_lshlrev_b32_e32 v4, 16, v113
	v_and_b32_e32 v5, 0xffff0000, v113
	v_pk_add_f32 v[124:125], v[124:125], v[4:5]
	v_lshlrev_b32_e32 v10, 16, v114
	v_and_b32_e32 v11, 0xffff0000, v114
	v_pk_add_f32 v[16:17], v[16:17], v[10:11]
	v_lshlrev_b32_e32 v4, 16, v115
	v_and_b32_e32 v5, 0xffff0000, v115
	v_pk_add_f32 v[14:15], v[14:15], v[4:5]
	v_lshlrev_b32_e32 v10, 16, v116
	v_and_b32_e32 v11, 0xffff0000, v116
	v_pk_add_f32 v[12:13], v[12:13], v[10:11]
	v_lshlrev_b32_e32 v4, 16, v117
	v_and_b32_e32 v5, 0xffff0000, v117
	v_pk_add_f32 v[124:125], v[124:125], v[4:5]
	v_lshlrev_b32_e32 v10, 16, v118
	v_and_b32_e32 v11, 0xffff0000, v118
	v_pk_add_f32 v[16:17], v[16:17], v[10:11]
	v_lshlrev_b32_e32 v4, 16, v119
	v_and_b32_e32 v5, 0xffff0000, v119
	v_pk_add_f32 v[14:15], v[14:15], v[4:5]
	v_lshlrev_b32_e32 v10, 16, v120
	v_and_b32_e32 v11, 0xffff0000, v120
	v_pk_add_f32 v[12:13], v[12:13], v[10:11]
	v_lshlrev_b32_e32 v4, 16, v121
	v_and_b32_e32 v5, 0xffff0000, v121
	v_pk_add_f32 v[124:125], v[124:125], v[4:5]
	v_lshlrev_b32_e32 v10, 16, v122
	v_and_b32_e32 v11, 0xffff0000, v122
	v_pk_add_f32 v[16:17], v[16:17], v[10:11]
	v_lshlrev_b32_e32 v4, 16, v123
	v_and_b32_e32 v5, 0xffff0000, v123
	v_pk_add_f32 v[14:15], v[14:15], v[4:5]
	s_mov_b64 exec, vcc
